# attention P*V section rewritten by hand: V fragments read 2 k-steps ahead, packed exp-sum tree, immediate LDS offsets, fixed accumulators
# speedup vs baseline: 1.0650x; 1.0063x over previous
.LBB0_412:
	v_add_u32_e32 v230, v182, v183
	v_add_u32_e32 v231, v182, v184
	v_add_u32_e32 v232, v182, v185
	v_add_u32_e32 v233, v182, v174
	v_add_u32_e32 v230, 0xe000, v230
	v_add_u32_e32 v231, 0xe000, v231
	v_add_u32_e32 v232, 0xe000, v232
	v_add_u32_e32 v233, 0xe000, v233
	ds_read2_b64 v[106:109], v230 offset0:32 offset1:36
	ds_read2_b64 v[110:113], v231 offset0:32 offset1:36
	ds_read2_b64 v[114:117], v232 offset0:32 offset1:36
	ds_read2_b64 v[118:121], v233 offset0:32 offset1:36
	ds_read2_b64 v[234:237], v230 offset0:40 offset1:44
	ds_read2_b64 v[238:241], v231 offset0:40 offset1:44
	ds_read2_b64 v[242:245], v232 offset0:40 offset1:44
	ds_read2_b64 v[246:249], v233 offset0:40 offset1:44
	v_pk_add_f32 v[228:229], v[0:1], v[42:43]
	v_pk_add_f32 v[102:103], v[36:37], v[44:45]
	v_pk_add_f32 v[104:105], v[38:39], v[46:47]
	v_pk_add_f32 v[250:251], v[40:41], v[48:49]
	v_pk_add_f32 v[228:229], v[228:229], v[50:51]
	v_pk_add_f32 v[102:103], v[102:103], v[52:53]
	v_pk_add_f32 v[104:105], v[104:105], v[54:55]
	v_pk_add_f32 v[250:251], v[250:251], v[56:57]
	v_pk_add_f32 v[228:229], v[228:229], v[58:59]
	v_pk_add_f32 v[102:103], v[102:103], v[60:61]
	v_pk_add_f32 v[104:105], v[104:105], v[62:63]
	v_pk_add_f32 v[250:251], v[250:251], v[64:65]
	v_pk_add_f32 v[228:229], v[228:229], v[66:67]
	v_pk_add_f32 v[102:103], v[102:103], v[68:69]
	v_pk_add_f32 v[104:105], v[104:105], v[70:71]
	v_pk_add_f32 v[250:251], v[250:251], v[72:73]
	v_pk_add_f32 v[228:229], v[228:229], v[74:75]
	v_pk_add_f32 v[102:103], v[102:103], v[76:77]
	v_pk_add_f32 v[104:105], v[104:105], v[78:79]
	v_pk_add_f32 v[250:251], v[250:251], v[80:81]
	v_pk_add_f32 v[228:229], v[228:229], v[82:83]
	v_pk_add_f32 v[102:103], v[102:103], v[84:85]
	v_pk_add_f32 v[104:105], v[104:105], v[86:87]
	v_pk_add_f32 v[250:251], v[250:251], v[88:89]
	v_pk_add_f32 v[228:229], v[228:229], v[90:91]
	v_pk_add_f32 v[102:103], v[102:103], v[92:93]
	v_pk_add_f32 v[228:229], v[228:229], v[102:103]
	v_pk_add_f32 v[104:105], v[104:105], v[250:251]
	v_pk_add_f32 v[228:229], v[228:229], v[104:105]
	v_add_f32_e32 v228, v228, v3
	v_add_f32_e32 v229, v229, v163
	v_add_f32_e32 v228, v228, v165
	v_add_f32_e32 v229, v229, v167
	v_add_f32_e32 v228, v228, v94
	v_add_f32_e32 v229, v229, v96
	v_add_f32_e32 v228, v228, v98
	v_add_f32_e32 v229, v229, v100
	v_add_f32_e32 v162, v228, v229
	ds_bpermute_b32 v95, v129, v162
	v_cvt_pk_bf16_f32 v102, v165, v163
	v_cvt_pk_bf16_f32 v103, v167, v93
	v_cvt_pk_bf16_f32 v104, v90, v89
	v_cvt_pk_bf16_f32 v105, v92, v91
	v_sub_f32_e32 v97, v135, v137
	v_exp_f32_e32 v97, v97
	s_waitcnt lgkmcnt(0)
	v_add_f32_e32 v162, v162, v95
	ds_bpermute_b32 v95, v131, v162
	v_cvt_pk_bf16_f32 v250, v86, v85
	v_cvt_pk_bf16_f32 v251, v88, v87
	v_cvt_pk_bf16_f32 v252, v82, v81
	v_cvt_pk_bf16_f32 v253, v84, v83
	s_waitcnt lgkmcnt(0)
	v_add_f32_e32 v162, v162, v95
	v_add_f32_e32 v95, v97, v162
	v_mfma_f32_16x16x32_bf16 v[164:167], v[106:109], v[102:105], 0
	v_mfma_f32_16x16x32_bf16 v[90:93], v[110:113], v[102:105], 0
	v_mfma_f32_16x16x32_bf16 v[82:85], v[114:117], v[102:105], 0
	v_mfma_f32_16x16x32_bf16 v[86:89], v[118:121], v[102:105], 0
	ds_read2_b64 v[106:109], v230 offset0:48 offset1:52
	ds_read2_b64 v[110:113], v231 offset0:48 offset1:52
	ds_read2_b64 v[114:117], v232 offset0:48 offset1:52
	ds_read2_b64 v[118:121], v233 offset0:48 offset1:52
	v_cvt_pk_bf16_f32 v102, v68, v65
	v_cvt_pk_bf16_f32 v103, v72, v69
	v_cvt_pk_bf16_f32 v104, v74, v73
	v_cvt_pk_bf16_f32 v105, v80, v79
	v_mfma_f32_16x16x32_bf16 v[164:167], v[234:237], v[250:253], v[164:167]
	v_mfma_f32_16x16x32_bf16 v[90:93], v[238:241], v[250:253], v[90:93]
	v_mfma_f32_16x16x32_bf16 v[82:85], v[242:245], v[250:253], v[82:85]
	v_mfma_f32_16x16x32_bf16 v[86:89], v[246:249], v[250:253], v[86:89]
	ds_read2_b64 v[234:237], v230 offset0:56 offset1:60
	ds_read2_b64 v[238:241], v231 offset0:56 offset1:60
	ds_read2_b64 v[242:245], v232 offset0:56 offset1:60
	ds_read2_b64 v[246:249], v233 offset0:56 offset1:60
	v_cvt_pk_bf16_f32 v250, v58, v57
	v_cvt_pk_bf16_f32 v251, v64, v61
	v_cvt_pk_bf16_f32 v252, v66, v63
	v_cvt_pk_bf16_f32 v253, v70, v67
	s_waitcnt lgkmcnt(4)
	v_mfma_f32_16x16x32_bf16 v[164:167], v[106:109], v[102:105], v[164:167]
	v_mfma_f32_16x16x32_bf16 v[90:93], v[110:113], v[102:105], v[90:93]
	v_mfma_f32_16x16x32_bf16 v[82:85], v[114:117], v[102:105], v[82:85]
	v_mfma_f32_16x16x32_bf16 v[86:89], v[118:121], v[102:105], v[86:89]
	ds_read2_b64 v[106:109], v230 offset0:64 offset1:68
	ds_read2_b64 v[110:113], v231 offset0:64 offset1:68
	ds_read2_b64 v[114:117], v232 offset0:64 offset1:68
	ds_read2_b64 v[118:121], v233 offset0:64 offset1:68
	v_cvt_pk_bf16_f32 v102, v50, v49
	v_cvt_pk_bf16_f32 v103, v54, v53
	v_cvt_pk_bf16_f32 v104, v56, v55
	v_cvt_pk_bf16_f32 v105, v62, v59
	s_waitcnt lgkmcnt(4)
	v_mfma_f32_16x16x32_bf16 v[164:167], v[234:237], v[250:253], v[164:167]
	v_mfma_f32_16x16x32_bf16 v[90:93], v[238:241], v[250:253], v[90:93]
	v_mfma_f32_16x16x32_bf16 v[82:85], v[242:245], v[250:253], v[82:85]
	v_mfma_f32_16x16x32_bf16 v[86:89], v[246:249], v[250:253], v[86:89]
	ds_read2_b64 v[234:237], v230 offset0:72 offset1:76
	ds_read2_b64 v[238:241], v231 offset0:72 offset1:76
	ds_read2_b64 v[242:245], v232 offset0:72 offset1:76
	ds_read2_b64 v[246:249], v233 offset0:72 offset1:76
	v_cvt_pk_bf16_f32 v250, v42, v41
	v_cvt_pk_bf16_f32 v251, v46, v45
	v_cvt_pk_bf16_f32 v252, v48, v47
	v_cvt_pk_bf16_f32 v253, v52, v51
	s_waitcnt lgkmcnt(4)
	v_mfma_f32_16x16x32_bf16 v[164:167], v[106:109], v[102:105], v[164:167]
	v_mfma_f32_16x16x32_bf16 v[90:93], v[110:113], v[102:105], v[90:93]
	v_mfma_f32_16x16x32_bf16 v[82:85], v[114:117], v[102:105], v[82:85]
	v_mfma_f32_16x16x32_bf16 v[86:89], v[118:121], v[102:105], v[86:89]
	ds_read2_b64 v[106:109], v230 offset0:80 offset1:84
	ds_read2_b64 v[110:113], v231 offset0:80 offset1:84
	ds_read2_b64 v[114:117], v232 offset0:80 offset1:84
	ds_read2_b64 v[118:121], v233 offset0:80 offset1:84
	v_cvt_pk_bf16_f32 v102, v36, v3
	v_cvt_pk_bf16_f32 v103, v38, v37
	v_cvt_pk_bf16_f32 v104, v40, v39
	v_cvt_pk_bf16_f32 v105, v44, v43
	s_waitcnt lgkmcnt(4)
	v_mfma_f32_16x16x32_bf16 v[164:167], v[234:237], v[250:253], v[164:167]
	v_mfma_f32_16x16x32_bf16 v[90:93], v[238:241], v[250:253], v[90:93]
	v_mfma_f32_16x16x32_bf16 v[82:85], v[242:245], v[250:253], v[82:85]
	v_mfma_f32_16x16x32_bf16 v[86:89], v[246:249], v[250:253], v[86:89]
	ds_read2_b64 v[234:237], v230 offset0:88 offset1:92
	ds_read2_b64 v[238:241], v231 offset0:88 offset1:92
	ds_read2_b64 v[242:245], v232 offset0:88 offset1:92
	ds_read2_b64 v[246:249], v233 offset0:88 offset1:92
	v_cvt_pk_bf16_f32 v250, v0, v1
	v_cvt_pk_bf16_f32 v251, v60, v71
	v_cvt_pk_bf16_f32 v252, v76, v75
	v_cvt_pk_bf16_f32 v253, v78, v77
	v_rcp_f32_e32 v56, v95
	s_waitcnt lgkmcnt(4)
	v_mfma_f32_16x16x32_bf16 v[164:167], v[106:109], v[102:105], v[164:167]
	v_mfma_f32_16x16x32_bf16 v[90:93], v[110:113], v[102:105], v[90:93]
	v_mfma_f32_16x16x32_bf16 v[82:85], v[114:117], v[102:105], v[82:85]
	v_mfma_f32_16x16x32_bf16 v[86:89], v[118:121], v[102:105], v[86:89]
	ds_read2_b64 v[106:109], v230 offset0:96 offset1:100
	ds_read2_b64 v[110:113], v231 offset0:96 offset1:100
	ds_read2_b64 v[114:117], v232 offset0:96 offset1:100
	ds_read2_b64 v[118:121], v233 offset0:96 offset1:100
	v_cvt_pk_bf16_f32 v102, v96, v94
	v_cvt_pk_bf16_f32 v103, v100, v98
	v_mov_b32_e32 v104, v2
	v_mov_b32_e32 v105, v2
	s_waitcnt lgkmcnt(4)
	v_mfma_f32_16x16x32_bf16 v[164:167], v[234:237], v[250:253], v[164:167]
	v_mfma_f32_16x16x32_bf16 v[90:93], v[238:241], v[250:253], v[90:93]
	v_mfma_f32_16x16x32_bf16 v[82:85], v[242:245], v[250:253], v[82:85]
	v_mfma_f32_16x16x32_bf16 v[86:89], v[246:249], v[250:253], v[86:89]
	s_waitcnt lgkmcnt(0)
	v_mfma_f32_16x16x32_bf16 v[40:43], v[106:109], v[102:105], v[164:167]
	v_mfma_f32_16x16x32_bf16 v[44:47], v[110:113], v[102:105], v[90:93]
	v_mfma_f32_16x16x32_bf16 v[48:51], v[114:117], v[102:105], v[82:85]
	v_mfma_f32_16x16x32_bf16 v[36:39], v[118:121], v[102:105], v[86:89]
	v_mov_b32_e32 v3, v2
	s_nop 3
	v_mul_f32_e64 v40, v56, v40
	v_mul_f32_e64 v41, v56, v41
	v_pk_mul_f32 v[0:1], v[56:57], v[42:43] op_sel_hi:[0,1]
	v_pk_mul_f32 v[42:43], v[40:41], v[40:41]
	v_cvt_pk_bf16_f32 v40, v40, v41
	v_cvt_pk_bf16_f32 v41, v0, v1
	v_pk_mul_f32 v[52:53], v[0:1], v[0:1]
	global_store_dwordx2 v[160:161], v[40:41], off offset:-64
	v_pk_mul_f32 v[0:1], v[56:57], v[46:47] op_sel_hi:[0,1]
	v_pk_mul_f32 v[40:41], v[56:57], v[44:45] op_sel_hi:[0,1]
	v_pk_mov_b32 v[54:55], v[42:43], v[52:53] op_sel:[1,0]
	v_mov_b32_e32 v43, v53
	v_pk_mul_f32 v[44:45], v[40:41], v[40:41]
	v_pk_mul_f32 v[46:47], v[0:1], v[0:1]
	v_pk_add_f32 v[42:43], v[54:55], v[42:43]
	v_pk_mov_b32 v[52:53], v[44:45], v[46:47] op_sel:[1,0]
	v_mov_b32_e32 v45, v47
	v_add_f32_e32 v3, v42, v43
	v_pk_add_f32 v[44:45], v[52:53], v[44:45]
	v_pk_mul_f32 v[36:37], v[56:57], v[36:37] op_sel_hi:[0,1]
	v_add_f32_e32 v42, v133, v3
	v_cvt_pk_bf16_f32 v40, v40, v41
	v_cvt_pk_bf16_f32 v41, v0, v1
	v_mul_f32_e32 v3, v37, v37
	v_pk_add_f32 v[44:45], v[44:45], v[44:45] op_sel:[0,1] op_sel_hi:[1,0]
	global_store_dwordx2 v[160:161], v[40:41], off offset:-32
	v_pk_mul_f32 v[40:41], v[56:57], v[48:49] op_sel_hi:[0,1]
	v_mul_f32_e32 v43, v36, v36
	v_mov_b32_e32 v45, v3
	v_pk_mul_f32 v[0:1], v[56:57], v[50:51] op_sel_hi:[0,1]
	v_pk_add_f32 v[42:43], v[42:43], v[44:45]
	v_mul_f32_e32 v44, v41, v41
	v_cvt_pk_bf16_f32 v46, v40, v41
	v_cvt_pk_bf16_f32 v47, v0, v1
	v_pk_mul_f32 v[38:39], v[56:57], v[38:39] op_sel_hi:[0,1]
	v_pk_fma_f32 v[40:41], v[40:41], v[40:41], v[44:45] op_sel_hi:[1,1,0]
	v_mul_f32_e32 v44, v1, v1
	global_store_dwordx2 v[160:161], v[46:47], off
	v_mul_f32_e32 v46, v38, v38
	v_mul_f32_e32 v47, v39, v39
	v_pk_fma_f32 v[0:1], v[0:1], v[0:1], v[44:45] op_sel_hi:[1,1,0]
	v_mov_b32_e32 v41, v46
	v_mov_b32_e32 v1, v47
	v_pk_add_f32 v[0:1], v[40:41], v[0:1]
	s_add_i32 s64, s64, 64
	v_pk_add_f32 v[0:1], v[42:43], v[0:1]
	s_cmpk_eq_i32 s64, 0x100
	v_add_f32_e32 v133, v0, v1
	v_cvt_pk_bf16_f32 v0, v36, v37
	v_cvt_pk_bf16_f32 v1, v38, v39
	global_store_dwordx2 v[160:161], v[0:1], off offset:32
	v_lshl_add_u64 v[160:161], v[160:161], 0, s[50:51]
	s_cbranch_scc1 .LBB0_414
	s_waitcnt vmcnt(4)
	v_mov_b64_e32 v[38:39], v[34:35]
	v_mov_b64_e32 v[36:37], v[32:33]
	s_branch .LBB0_408
